# k9: sample units no longer wait for band-shift stores before staging; static unit order rebalanced (4 big units, or 3 big + sample, or 3 big + 2 small per workgroup)
# speedup vs baseline: 1.0180x; 1.0050x over previous
.LBB9_84:
	s_andn2_b64 vcc, exec, s[4:5]
	s_cbranch_vccnz .LBB9_172
	s_and_b32 s48, s2, 31
	s_lshr_b32 s49, s2, 5
	v_mbcnt_lo_u32_b32 v2, -1, 0
	s_mov_b32 s13, 0
	s_movk_i32 s50, 0x1800
	s_movk_i32 s51, 0x500
	s_movk_i32 s52, 0x1ff
	s_add_i32 s53, 0, 0x12c00
	s_movk_i32 s54, 0x27f
	s_mov_b32 s14, 0x3fb8aa3b
	s_movk_i32 s55, 0xc00
	s_add_i32 s56, 0, 0x13400
	s_movk_i32 s57, 0x2ff
	v_mov_b32_e32 v69, 0
	s_mov_b64 s[16:17], 0x20000
	s_movk_i32 s58, 0x110
	s_mov_b32 s59, 0x41000000
	s_mov_b64 s[18:19], 0xd700000
	s_mov_b32 s60, 0xd700000
	v_mov_b32_e32 v1, 0xfffffd80
	v_mov_b32_e32 v131, 0xc1
	v_mov_b32_e32 v133, 0x2c2
	v_mbcnt_hi_u32_b32 v139, -1, v2
	s_mov_b32 s74, 0
	s_mov_b32 s61, 0
	s_branch .LBB9_88

.LBB9_88:
	s_cmp_lt_u32 s49, 4
	s_cbranch_scc0 .Lodd_g_hi
	s_cmp_gt_u32 s61, 3
	s_cbranch_scc1 .Lodd_none
	s_lshl_b32 s62, s61, 2
	s_add_i32 s62, s62, s49
	s_add_i32 s62, s62, 4
	s_branch .Lodd_prompt
.Lodd_g_hi:
	s_cmp_gt_u32 s61, 2
	s_cbranch_scc1 .Lodd_extra
	s_lshl_b32 s62, s61, 2
	s_add_i32 s62, s62, s49
	s_add_i32 s62, s62, 16
	s_branch .Lodd_prompt
.Lodd_extra:
	s_cmp_gt_u32 s61, 4
	s_cbranch_scc1 .Lodd_none
	s_cmp_gt_u32 s49, 5
	s_cbranch_scc1 .Lodd_small
	s_cmp_eq_u32 s61, 3
	s_cbranch_scc0 .Lodd_none
	s_lshl_b32 s62, s48, 1
	s_add_i32 s62, s62, s49
	s_add_i32 s62, s62, 0x3fc
	s_branch .LBB9_93
.Lodd_small:
	s_sub_i32 s62, 9, s49
	s_sub_i32 s2, s49, 6
	s_cmp_eq_u32 s61, 3
	s_cselect_b32 s62, s62, s2
.Lodd_prompt:
	s_lshl_b32 s62, s62, 5
	s_or_b32 s62, s62, s48
	s_branch .LBB9_93
.Lodd_none:
	s_mov_b32 s62, -1

.LBB9_138:
	s_cmp_lt_i32 s69, s41
	s_cselect_b64 s[38:39], -1, 0
	s_cmp_ge_i32 s69, s41
	s_cbranch_scc1 .LBB9_144
	s_add_i32 s12, s68, 1
	s_cmp_ge_i32 s12, s63
	s_cbranch_scc1 .LBB9_143
	v_subrev_u32_e32 v70, 64, v136
	v_mad_i64_i32 v[36:37], s[36:37], s28, v70, 0
	v_or_b32_e32 v36, v36, v130
	v_lshlrev_b64 v[48:49], 2, v[36:37]
	v_lshl_add_u64 v[44:45], s[24:25], 0, v[48:49]
	s_lshl_b32 s12, s46, 2
	v_lshl_add_u64 v[56:57], s[26:27], 0, v[48:49]
	v_lshl_add_u64 v[50:51], v[44:45], 0, s[12:13]
	v_lshl_add_u64 v[64:65], v[56:57], 0, s[12:13]
	global_load_dwordx4 v[36:39], v[44:45], off offset:16
	global_load_dwordx4 v[40:43], v[44:45], off
	s_nop 0
	global_load_dwordx4 v[44:47], v[50:51], off offset:16
	global_load_dwordx4 v[52:55], v[50:51], off
	s_nop 0
	global_load_dwordx4 v[48:51], v[56:57], off offset:16
	global_load_dwordx4 v[60:63], v[56:57], off
	s_nop 0
	global_load_dwordx4 v[56:59], v[64:65], off offset:16
	s_nop 0
	global_load_dwordx4 v[64:67], v[64:65], off
	s_cmp_lt_i32 s68, 0
	s_cselect_b64 s[36:37], -1, 0
	s_xor_b64 s[72:73], s[4:5], -1
	s_or_b64 s[36:37], s[72:73], s[36:37]
	s_and_b64 vcc, exec, s[36:37]
	s_cbranch_vccnz .LBB9_142
	v_ashrrev_i32_e32 v71, 31, v70
	v_lshlrev_b64 v[70:71], 12, v[70:71]
	v_lshl_or_b32 v70, v130, 2, v70
	s_waitcnt vmcnt(11)
	v_lshl_add_u64 v[88:89], s[30:31], 0, v[70:71]
	s_waitcnt vmcnt(6)
	global_store_dwordx4 v[88:89], v[40:43], off
	global_store_dwordx4 v[88:89], v[36:39], off offset:16
	v_lshl_add_u64 v[90:91], v[88:89], 0, s[16:17]
	v_add_co_u32_e32 v88, vcc, 0x20000, v88
	v_lshl_add_u64 v[70:71], s[34:35], 0, v[70:71]
	s_nop 0
	v_addc_co_u32_e32 v89, vcc, 0, v89, vcc
	s_waitcnt vmcnt(6)
	global_store_dwordx4 v[88:89], v[52:55], off
	global_store_dwordx4 v[90:91], v[44:47], off offset:16
	s_waitcnt vmcnt(6)
	global_store_dwordx4 v[70:71], v[60:63], off
	global_store_dwordx4 v[70:71], v[48:51], off offset:16
	v_lshl_add_u64 v[88:89], v[70:71], 0, s[16:17]
	v_add_co_u32_e32 v70, vcc, 0x20000, v70
	s_nop 1
	v_addc_co_u32_e32 v71, vcc, 0, v71, vcc
	s_waitcnt vmcnt(6)
	global_store_dwordx4 v[70:71], v[64:67], off
	global_store_dwordx4 v[88:89], v[56:59], off offset:16
	s_nop 1
	v_cvt_pk_bf16_f32 v88, v40, v41
	v_cvt_pk_bf16_f32 v89, v42, v43
	v_cvt_pk_bf16_f32 v90, v36, v37
	v_cvt_pk_bf16_f32 v91, v38, v39
	v_cvt_pk_bf16_f32 v92, v52, v53
	v_cvt_pk_bf16_f32 v93, v54, v55
	v_cvt_pk_bf16_f32 v94, v44, v45
	v_cvt_pk_bf16_f32 v95, v46, v47
	v_cvt_pk_bf16_f32 v96, v60, v61
	v_cvt_pk_bf16_f32 v97, v62, v63
	v_cvt_pk_bf16_f32 v98, v48, v49
	v_cvt_pk_bf16_f32 v99, v50, v51
	v_cvt_pk_bf16_f32 v100, v64, v65
	v_cvt_pk_bf16_f32 v101, v66, v67
	v_cvt_pk_bf16_f32 v102, v56, v57
	v_cvt_pk_bf16_f32 v103, v58, v59
	ds_write_b128 v132, v[88:91] offset:17408
	ds_write_b128 v132, v[92:95] offset:26112
	ds_write_b128 v135, v[96:99]
	ds_write_b128 v135, v[100:103] offset:10240
	s_branch .LBB9_144

.LBB9_157:
	s_andn2_b64 vcc, exec, s[8:9]
	s_cbranch_vccnz .LBB9_163
	s_add_i32 s8, s68, 2
	s_cmp_ge_i32 s8, s63
	s_cbranch_scc1 .LBB9_162
	v_mad_i64_i32 v[36:37], s[8:9], s28, v136, 0
	v_or_b32_e32 v36, v36, v130
	v_lshlrev_b64 v[48:49], 2, v[36:37]
	v_lshl_add_u64 v[44:45], s[24:25], 0, v[48:49]
	s_lshl_b32 s12, s46, 2
	v_lshl_add_u64 v[56:57], s[26:27], 0, v[48:49]
	v_lshl_add_u64 v[50:51], v[44:45], 0, s[12:13]
	v_lshl_add_u64 v[64:65], v[56:57], 0, s[12:13]
	global_load_dwordx4 v[36:39], v[44:45], off offset:16
	global_load_dwordx4 v[40:43], v[44:45], off
	s_nop 0
	global_load_dwordx4 v[44:47], v[50:51], off offset:16
	global_load_dwordx4 v[52:55], v[50:51], off
	s_nop 0
	global_load_dwordx4 v[48:51], v[56:57], off offset:16
	global_load_dwordx4 v[60:63], v[56:57], off
	s_nop 0
	global_load_dwordx4 v[56:59], v[64:65], off offset:16
	s_nop 0
	global_load_dwordx4 v[64:67], v[64:65], off
	s_cmp_lt_i32 s68, -1
	s_cselect_b64 s[8:9], -1, 0
	s_xor_b64 s[36:37], s[4:5], -1
	s_or_b64 s[8:9], s[36:37], s[8:9]
	s_and_b64 vcc, exec, s[8:9]
	s_cbranch_vccnz .LBB9_161
	v_ashrrev_i32_e32 v137, 31, v136
	v_lshlrev_b64 v[70:71], 12, v[136:137]
	v_lshl_or_b32 v70, v130, 2, v70
	s_waitcnt vmcnt(11)
	v_lshl_add_u64 v[104:105], s[30:31], 0, v[70:71]
	s_waitcnt vmcnt(6)
	global_store_dwordx4 v[104:105], v[40:43], off
	global_store_dwordx4 v[104:105], v[36:39], off offset:16
	v_lshl_add_u64 v[106:107], v[104:105], 0, s[16:17]
	v_add_co_u32_e32 v104, vcc, 0x20000, v104
	v_lshl_add_u64 v[70:71], s[34:35], 0, v[70:71]
	s_nop 0
	v_addc_co_u32_e32 v105, vcc, 0, v105, vcc
	s_waitcnt vmcnt(6)
	global_store_dwordx4 v[104:105], v[52:55], off
	global_store_dwordx4 v[106:107], v[44:47], off offset:16
	s_waitcnt vmcnt(6)
	global_store_dwordx4 v[70:71], v[60:63], off
	global_store_dwordx4 v[70:71], v[48:51], off offset:16
	v_lshl_add_u64 v[104:105], v[70:71], 0, s[16:17]
	v_add_co_u32_e32 v70, vcc, 0x20000, v70
	s_nop 1
	v_addc_co_u32_e32 v71, vcc, 0, v71, vcc
	s_waitcnt vmcnt(6)
	global_store_dwordx4 v[70:71], v[64:67], off
	global_store_dwordx4 v[104:105], v[56:59], off offset:16
	s_nop 1
	v_cvt_pk_bf16_f32 v104, v40, v41
	v_cvt_pk_bf16_f32 v105, v42, v43
	v_cvt_pk_bf16_f32 v106, v36, v37
	v_cvt_pk_bf16_f32 v107, v38, v39
	v_cvt_pk_bf16_f32 v108, v52, v53
	v_cvt_pk_bf16_f32 v109, v54, v55
	v_cvt_pk_bf16_f32 v110, v44, v45
	v_cvt_pk_bf16_f32 v111, v46, v47
	v_cvt_pk_bf16_f32 v112, v60, v61
	v_cvt_pk_bf16_f32 v113, v62, v63
	v_cvt_pk_bf16_f32 v114, v48, v49
	v_cvt_pk_bf16_f32 v115, v50, v51
	v_cvt_pk_bf16_f32 v116, v64, v65
	v_cvt_pk_bf16_f32 v117, v66, v67
	v_cvt_pk_bf16_f32 v118, v56, v57
	v_cvt_pk_bf16_f32 v119, v58, v59
	ds_write_b128 v132, v[104:107]
	ds_write_b128 v132, v[108:111] offset:8704
	ds_write_b128 v134, v[112:115] offset:34816
	ds_write_b128 v134, v[116:119] offset:45056
	s_branch .LBB9_163
